# sample-group LRU scan pipelined (prefetched row pairs); LRU read-outs issue all LDS reads up front
# baseline (speedup 1.0000x reference)
.LBB0_743:
	s_or_b64 exec, exec, s[14:15]
	v_lshlrev_b32_e32 v0, 2, v66
	v_ashrrev_i32_e32 v6, 3, v66
	v_and_b32_e32 v0, 0xfc, v0
	v_and_b32_e32 v7, -8, v6
	v_lshl_add_u32 v8, v0, 2, s0
	s_lshl_b32 s1, s1, 11
	v_lshl_add_u32 v2, v7, 10, v8
	s_or_b32 s1, s1, s89
	s_xor_b64 s[14:15], s[12:13], -1
	s_waitcnt lgkmcnt(0)
	s_barrier
	ds_read_b128 v[68:71], v2
	ds_read_b128 v[72:75], v2 offset:1024
	ds_read_b128 v[76:79], v2 offset:2048
	ds_read_b128 v[80:83], v2 offset:3072
	ds_read_b128 v[84:87], v2 offset:4096
	ds_read_b128 v[88:91], v2 offset:5120
	ds_read_b128 v[92:95], v2 offset:6144
	ds_read_b128 v[96:99], v2 offset:7168
	v_lshlrev_b32_e32 v184, 1, v0
	v_lshl_add_u64 v[0:1], s[10:11], 0, v[184:185]
	v_add_u32_e32 v100, s1, v7
	v_mad_i64_i32 v[100:101], s[12:13], v100, s68, v[0:1]
	s_waitcnt lgkmcnt(7)
	v_cvt_pk_bf16_f32 v68, v68, v69
	v_cvt_pk_bf16_f32 v69, v70, v71
	global_store_dwordx2 v[100:101], v[68:69], off
	v_or_b32_e32 v9, 1, v7
	v_add_u32_e32 v102, s1, v9
	v_mad_i64_i32 v[102:103], s[12:13], v102, s68, v[0:1]
	s_waitcnt lgkmcnt(6)
	v_cvt_pk_bf16_f32 v72, v72, v73
	v_cvt_pk_bf16_f32 v73, v74, v75
	global_store_dwordx2 v[102:103], v[72:73], off
	v_or_b32_e32 v9, 2, v7
	v_add_u32_e32 v100, s1, v9
	v_mad_i64_i32 v[100:101], s[12:13], v100, s68, v[0:1]
	s_waitcnt lgkmcnt(5)
	v_cvt_pk_bf16_f32 v76, v76, v77
	v_cvt_pk_bf16_f32 v77, v78, v79
	global_store_dwordx2 v[100:101], v[76:77], off
	v_or_b32_e32 v9, 3, v7
	v_add_u32_e32 v102, s1, v9
	v_mad_i64_i32 v[102:103], s[12:13], v102, s68, v[0:1]
	s_waitcnt lgkmcnt(4)
	v_cvt_pk_bf16_f32 v80, v80, v81
	v_cvt_pk_bf16_f32 v81, v82, v83
	global_store_dwordx2 v[102:103], v[80:81], off
	v_or_b32_e32 v9, 4, v7
	v_add_u32_e32 v100, s1, v9
	v_mad_i64_i32 v[100:101], s[12:13], v100, s68, v[0:1]
	s_waitcnt lgkmcnt(3)
	v_cvt_pk_bf16_f32 v84, v84, v85
	v_cvt_pk_bf16_f32 v85, v86, v87
	global_store_dwordx2 v[100:101], v[84:85], off
	v_or_b32_e32 v9, 5, v7
	v_add_u32_e32 v102, s1, v9
	v_mad_i64_i32 v[102:103], s[12:13], v102, s68, v[0:1]
	s_waitcnt lgkmcnt(2)
	v_cvt_pk_bf16_f32 v88, v88, v89
	v_cvt_pk_bf16_f32 v89, v90, v91
	global_store_dwordx2 v[102:103], v[88:89], off
	v_or_b32_e32 v9, 6, v7
	v_add_u32_e32 v100, s1, v9
	v_mad_i64_i32 v[100:101], s[12:13], v100, s68, v[0:1]
	s_waitcnt lgkmcnt(1)
	v_cvt_pk_bf16_f32 v92, v92, v93
	v_cvt_pk_bf16_f32 v93, v94, v95
	global_store_dwordx2 v[100:101], v[92:93], off
	v_or_b32_e32 v9, 7, v7
	v_add_u32_e32 v102, s1, v9
	v_mad_i64_i32 v[102:103], s[12:13], v102, s68, v[0:1]
	s_waitcnt lgkmcnt(0)
	v_cvt_pk_bf16_f32 v96, v96, v97
	v_cvt_pk_bf16_f32 v97, v98, v99
	global_store_dwordx2 v[102:103], v[96:97], off
	s_mov_b32 s0, 1
	s_mov_b64 s[12:13], 0
	s_and_b64 vcc, exec, s[14:15]
	s_barrier
	s_cbranch_vccnz .LBB0_811

.LBB0_843:
	s_or_b64 exec, exec, s[10:11]
	v_mul_f32_e32 v44, 0xbfb8aa3b, v188
	v_mul_f32_e32 v46, 0xbfb8aa3b, v190
	v_fmamk_f32 v34, v76, 0xbfb8aa3b, v44
	v_fmamk_f32 v37, v80, 0xbfb8aa3b, v46
	v_mul_f32_e32 v33, 0xbfb8aa3b, v189
	v_min_f32_e32 v34, 0x42700000, v34
	v_min_f32_e32 v37, 0x42700000, v37
	v_exp_f32_e32 v33, v33
	v_exp_f32_e32 v34, v34
	v_exp_f32_e32 v37, v37
	s_waitcnt lgkmcnt(14)
	v_lshlrev_b32_e32 v35, 16, v35
	v_add_f32_e32 v33, 1.0, v33
	v_add_f32_e32 v34, 1.0, v34
	v_add_f32_e32 v37, 1.0, v37
	v_log_f32_e32 v33, v33
	v_mul_f32_e32 v38, v34, v37
	v_rcp_f32_e32 v38, v38
	v_fmamk_f32 v60, v60, 0xbfb8aa3b, v46
	v_mul_f32_e32 v33, 0x3f317218, v33
	v_mul_f32_e32 v53, 0xc138aa3b, v33
	v_mul_f32_e32 v33, v37, v38
	v_mul_f32_e32 v37, v34, v38
	v_lshlrev_b32_e32 v38, 16, v32
	v_fmamk_f32 v32, v77, 0xbfb8aa3b, v44
	v_min_f32_e32 v32, 0x42700000, v32
	v_exp_f32_e32 v34, v32
	v_fmamk_f32 v32, v81, 0xbfb8aa3b, v46
	v_min_f32_e32 v32, 0x42700000, v32
	v_exp_f32_e32 v41, v32
	v_mul_f32_e32 v32, v53, v33
	v_exp_f32_e32 v32, v32
	v_add_f32_e32 v42, 1.0, v34
	v_add_f32_e32 v33, 1.0, v41
	v_mul_f32_e32 v34, v42, v33
	v_rcp_f32_e32 v41, v34
	v_fma_f32 v34, -v32, v32, 1.0
	v_max_f32_e32 v34, 0, v34
	v_sqrt_f32_e32 v54, v34
	v_mul_f32_e32 v33, v33, v41
	v_mul_f32_e32 v33, v53, v33
	v_exp_f32_e32 v34, v33
	v_mul_f32_e32 v33, v37, v54
	v_mul_f32_e32 v37, v42, v41
	v_fmamk_f32 v41, v78, 0xbfb8aa3b, v44
	v_fmamk_f32 v42, v82, 0xbfb8aa3b, v46
	v_min_f32_e32 v41, 0x42700000, v41
	v_min_f32_e32 v42, 0x42700000, v42
	v_exp_f32_e32 v41, v41
	v_exp_f32_e32 v42, v42
	v_mul_f32_e32 v33, v33, v38
	v_fma_f32 v38, -v34, v34, 1.0
	v_max_f32_e32 v38, 0, v38
	v_add_f32_e32 v41, 1.0, v41
	v_add_f32_e32 v42, 1.0, v42
	v_sqrt_f32_e32 v38, v38
	v_mul_f32_e32 v54, v41, v42
	v_rcp_f32_e32 v54, v54
	v_min_f32_e32 v60, 0x42700000, v60
	v_mul_f32_e32 v37, v37, v38
	v_mul_f32_e32 v35, v37, v35
	v_mul_f32_e32 v37, v42, v54
	v_lshlrev_b32_e32 v42, 16, v36
	v_fmamk_f32 v36, v79, 0xbfb8aa3b, v44
	v_min_f32_e32 v36, 0x42700000, v36
	v_exp_f32_e32 v38, v36
	v_fmamk_f32 v36, v83, 0xbfb8aa3b, v46
	v_min_f32_e32 v36, 0x42700000, v36
	v_mul_f32_e32 v41, v41, v54
	v_exp_f32_e32 v54, v36
	v_mul_f32_e32 v36, v53, v37
	v_exp_f32_e32 v36, v36
	v_add_f32_e32 v76, 1.0, v38
	v_add_f32_e32 v37, 1.0, v54
	v_mul_f32_e32 v38, v76, v37
	v_rcp_f32_e32 v54, v38
	v_fma_f32 v38, -v36, v36, 1.0
	v_max_f32_e32 v38, 0, v38
	v_sqrt_f32_e32 v77, v38
	v_mul_f32_e32 v37, v37, v54
	v_mul_f32_e32 v37, v53, v37
	v_exp_f32_e32 v38, v37
	v_mul_f32_e32 v37, v41, v77
	v_mul_f32_e32 v41, v76, v54
	v_fmamk_f32 v54, v72, 0xbfb8aa3b, v44
	v_min_f32_e32 v54, 0x42700000, v54
	v_exp_f32_e32 v54, v54
	v_exp_f32_e32 v60, v60
	v_mul_f32_e32 v37, v37, v42
	v_fma_f32 v42, -v38, v38, 1.0
	v_max_f32_e32 v42, 0, v42
	v_add_f32_e32 v54, 1.0, v54
	v_add_f32_e32 v60, 1.0, v60
	v_sqrt_f32_e32 v42, v42
	v_mul_f32_e32 v72, v54, v60
	v_rcp_f32_e32 v72, v72
	v_lshlrev_b32_e32 v39, 16, v39
	v_mul_f32_e32 v41, v41, v42
	v_mul_f32_e32 v39, v41, v39
	v_mul_f32_e32 v41, v60, v72
	v_lshlrev_b32_e32 v60, 16, v40
	v_fmamk_f32 v40, v73, 0xbfb8aa3b, v44
	v_min_f32_e32 v40, 0x42700000, v40
	v_exp_f32_e32 v42, v40
	v_fmamk_f32 v40, v61, 0xbfb8aa3b, v46
	v_min_f32_e32 v40, 0x42700000, v40
	v_exp_f32_e32 v61, v40
	v_mul_f32_e32 v40, v53, v41
	v_exp_f32_e32 v40, v40
	v_mul_f32_e32 v54, v54, v72
	v_add_f32_e32 v72, 1.0, v42
	v_add_f32_e32 v41, 1.0, v61
	v_mul_f32_e32 v42, v72, v41
	v_rcp_f32_e32 v61, v42
	v_fma_f32 v42, -v40, v40, 1.0
	v_max_f32_e32 v42, 0, v42
	v_sqrt_f32_e32 v73, v42
	v_mul_f32_e32 v41, v41, v61
	v_mul_f32_e32 v41, v53, v41
	v_exp_f32_e32 v42, v41
	v_mul_f32_e32 v41, v54, v73
	v_mul_f32_e32 v54, v72, v61
	v_fmamk_f32 v61, v74, 0xbfb8aa3b, v44
	v_fmamk_f32 v62, v62, 0xbfb8aa3b, v46
	v_min_f32_e32 v61, 0x42700000, v61
	v_min_f32_e32 v62, 0x42700000, v62
	v_exp_f32_e32 v61, v61
	v_exp_f32_e32 v62, v62
	v_mul_f32_e32 v41, v41, v60
	v_fma_f32 v60, -v42, v42, 1.0
	v_max_f32_e32 v60, 0, v60
	v_sqrt_f32_e32 v60, v60
	v_add_f32_e32 v61, 1.0, v61
	v_add_f32_e32 v62, 1.0, v62
	v_mul_f32_e32 v72, v61, v62
	v_fmac_f32_e32 v44, 0xbfb8aa3b, v75
	v_rcp_f32_e32 v72, v72
	v_min_f32_e32 v44, 0x42700000, v44
	v_fmac_f32_e32 v46, 0xbfb8aa3b, v63
	v_mul_f32_e32 v54, v54, v60
	v_exp_f32_e32 v60, v44
	v_min_f32_e32 v44, 0x42700000, v46
	v_exp_f32_e32 v46, v44
	v_lshlrev_b32_e32 v43, 16, v43
	v_mul_f32_e32 v43, v54, v43
	v_mul_f32_e32 v54, v62, v72
	v_mul_f32_e32 v44, v53, v54
	v_exp_f32_e32 v44, v44
	v_add_f32_e32 v54, 1.0, v60
	v_add_f32_e32 v46, 1.0, v46
	v_mul_f32_e32 v60, v54, v46
	v_rcp_f32_e32 v60, v60
	v_fma_f32 v62, -v44, v44, 1.0
	v_max_f32_e32 v62, 0, v62
	v_sqrt_f32_e32 v62, v62
	v_mul_f32_e32 v46, v46, v60
	v_mul_f32_e32 v46, v53, v46
	v_exp_f32_e32 v46, v46
	v_mul_f32_e32 v53, v61, v72
	v_lshlrev_b32_e32 v45, 16, v45
	v_mul_f32_e32 v53, v53, v62
	v_mul_f32_e32 v62, 0xbfb8aa3b, v183
	v_mul_f32_e32 v63, 0xbfb8aa3b, v186
	v_mul_f32_e32 v45, v53, v45
	v_mul_f32_e32 v53, v54, v60
	v_fmamk_f32 v60, v68, 0xbfb8aa3b, v62
	v_fmamk_f32 v56, v56, 0xbfb8aa3b, v63
	v_fma_f32 v61, -v46, v46, 1.0
	v_mul_f32_e32 v54, 0xbfb8aa3b, v187
	v_min_f32_e32 v60, 0x42700000, v60
	v_min_f32_e32 v56, 0x42700000, v56
	v_max_f32_e32 v61, 0, v61
	v_exp_f32_e32 v54, v54
	v_exp_f32_e32 v60, v60
	v_exp_f32_e32 v56, v56
	v_sqrt_f32_e32 v61, v61
	v_add_f32_e32 v54, 1.0, v54
	v_add_f32_e32 v60, 1.0, v60
	v_add_f32_e32 v56, 1.0, v56
	v_mul_f32_e32 v53, v53, v61
	v_log_f32_e32 v54, v54
	v_mul_f32_e32 v61, v60, v56
	v_rcp_f32_e32 v61, v61
	v_lshlrev_b32_e32 v47, 16, v47
	v_mul_f32_e32 v47, v53, v47
	v_mul_f32_e32 v53, 0x3f317218, v54
	v_mul_f32_e32 v68, 0xc138aa3b, v53
	v_mul_f32_e32 v53, v56, v61
	v_mul_f32_e32 v56, v60, v61
	v_lshlrev_b32_e32 v60, 16, v52
	v_fmamk_f32 v52, v69, 0xbfb8aa3b, v62
	v_min_f32_e32 v52, 0x42700000, v52
	v_exp_f32_e32 v54, v52
	v_fmamk_f32 v52, v57, 0xbfb8aa3b, v63
	v_min_f32_e32 v52, 0x42700000, v52
	v_exp_f32_e32 v57, v52
	v_mul_f32_e32 v52, v68, v53
	v_exp_f32_e32 v52, v52
	v_add_f32_e32 v61, 1.0, v54
	v_add_f32_e32 v53, 1.0, v57
	v_mul_f32_e32 v54, v61, v53
	v_rcp_f32_e32 v57, v54
	v_fma_f32 v54, -v52, v52, 1.0
	v_max_f32_e32 v54, 0, v54
	v_sqrt_f32_e32 v69, v54
	v_mul_f32_e32 v53, v53, v57
	v_mul_f32_e32 v53, v68, v53
	v_exp_f32_e32 v54, v53
	v_mul_f32_e32 v53, v56, v69
	v_mul_f32_e32 v53, v53, v60
	v_fmamk_f32 v60, v70, 0xbfb8aa3b, v62
	v_fmamk_f32 v58, v58, 0xbfb8aa3b, v63
	v_min_f32_e32 v60, 0x42700000, v60
	v_min_f32_e32 v58, 0x42700000, v58
	v_exp_f32_e32 v60, v60
	v_exp_f32_e32 v58, v58
	v_mul_f32_e32 v56, v61, v57
	v_fma_f32 v57, -v54, v54, 1.0
	v_max_f32_e32 v57, 0, v57
	v_add_f32_e32 v60, 1.0, v60
	v_add_f32_e32 v58, 1.0, v58
	v_sqrt_f32_e32 v57, v57
	v_mul_f32_e32 v61, v60, v58
	v_rcp_f32_e32 v61, v61
	v_lshlrev_b32_e32 v55, 16, v55
	v_mul_f32_e32 v56, v56, v57
	v_mul_f32_e32 v55, v56, v55
	v_mul_f32_e32 v56, v58, v61
	v_fmamk_f32 v58, v71, 0xbfb8aa3b, v62
	v_fmamk_f32 v59, v59, 0xbfb8aa3b, v63
	v_min_f32_e32 v58, 0x42700000, v58
	v_min_f32_e32 v59, 0x42700000, v59
	v_exp_f32_e32 v58, v58
	v_exp_f32_e32 v59, v59
	v_mul_f32_e32 v57, v60, v61
	v_mul_f32_e32 v56, v68, v56
	v_add_f32_e32 v61, 1.0, v58
	v_add_f32_e32 v58, 1.0, v59
	v_exp_f32_e32 v56, v56
	v_mul_f32_e32 v59, v61, v58
	v_rcp_f32_e32 v59, v59
	v_fmamk_f32 v48, v48, 0xbfb8aa3b, v63
	v_fma_f32 v69, -v56, v56, 1.0
	v_max_f32_e32 v69, 0, v69
	v_mul_f32_e32 v58, v58, v59
	v_sqrt_f32_e32 v69, v69
	v_mul_f32_e32 v58, v68, v58
	v_exp_f32_e32 v58, v58
	v_mul_f32_e32 v59, v61, v59
	v_fmamk_f32 v61, v64, 0xbfb8aa3b, v62
	v_min_f32_e32 v61, 0x42700000, v61
	v_min_f32_e32 v48, 0x42700000, v48
	v_exp_f32_e32 v61, v61
	v_exp_f32_e32 v48, v48
	v_lshlrev_b32_e32 v60, 16, v114
	v_mul_f32_e32 v57, v57, v69
	v_mul_f32_e32 v57, v57, v60
	v_fma_f32 v60, -v58, v58, 1.0
	v_max_f32_e32 v60, 0, v60
	v_sqrt_f32_e32 v60, v60
	v_add_f32_e32 v61, 1.0, v61
	v_add_f32_e32 v48, 1.0, v48
	v_mul_f32_e32 v64, v61, v48
	v_rcp_f32_e32 v64, v64
	v_mul_f32_e32 v59, v59, v60
	v_fmamk_f32 v60, v65, 0xbfb8aa3b, v62
	v_fmamk_f32 v49, v49, 0xbfb8aa3b, v63
	v_min_f32_e32 v60, 0x42700000, v60
	v_min_f32_e32 v49, 0x42700000, v49
	v_mul_f32_e32 v48, v48, v64
	v_exp_f32_e32 v60, v60
	v_exp_f32_e32 v49, v49
	v_mul_f32_e32 v48, v68, v48
	v_exp_f32_e32 v48, v48
	v_add_f32_e32 v65, 1.0, v60
	v_add_f32_e32 v49, 1.0, v49
	v_lshlrev_b32_e32 v69, 16, v113
	v_mul_f32_e32 v60, v65, v49
	v_mul_f32_e32 v59, v59, v69
	v_rcp_f32_e32 v69, v60
	v_fma_f32 v60, -v48, v48, 1.0
	v_max_f32_e32 v60, 0, v60
	v_sqrt_f32_e32 v70, v60
	v_mul_f32_e32 v49, v49, v69
	v_mul_f32_e32 v61, v61, v64
	v_mul_f32_e32 v49, v68, v49
	v_exp_f32_e32 v60, v49
	v_mul_f32_e32 v49, v61, v70
	v_mul_f32_e32 v61, v65, v69
	v_fmamk_f32 v65, v66, 0xbfb8aa3b, v62
	v_fmamk_f32 v50, v50, 0xbfb8aa3b, v63
	v_min_f32_e32 v65, 0x42700000, v65
	v_min_f32_e32 v50, 0x42700000, v50
	v_exp_f32_e32 v65, v65
	v_exp_f32_e32 v50, v50
	v_fmac_f32_e32 v62, 0xbfb8aa3b, v67
	v_fmac_f32_e32 v63, 0xbfb8aa3b, v51
	v_add_f32_e32 v65, 1.0, v65
	v_add_f32_e32 v50, 1.0, v50
	v_lshlrev_b32_e32 v64, 16, v112
	v_mul_f32_e32 v66, v65, v50
	v_min_f32_e32 v62, 0x42700000, v62
	v_min_f32_e32 v51, 0x42700000, v63
	v_mul_f32_e32 v49, v49, v64
	v_fma_f32 v64, -v60, v60, 1.0
	v_rcp_f32_e32 v66, v66
	v_exp_f32_e32 v62, v62
	v_exp_f32_e32 v51, v51
	v_max_f32_e32 v64, 0, v64
	v_sqrt_f32_e32 v64, v64
	v_mul_f32_e32 v50, v50, v66
	v_add_f32_e32 v63, 1.0, v62
	v_add_f32_e32 v51, 1.0, v51
	v_mul_f32_e32 v50, v68, v50
	v_mul_f32_e32 v62, v63, v51
	v_mul_f32_e32 v61, v61, v64
	v_exp_f32_e32 v50, v50
	v_rcp_f32_e32 v64, v62
	v_lshlrev_b32_e32 v69, 16, v111
	v_mul_f32_e32 v61, v61, v69
	v_fma_f32 v62, -v50, v50, 1.0
	v_mul_f32_e32 v51, v51, v64
	v_max_f32_e32 v62, 0, v62
	v_mul_f32_e32 v51, v68, v51
	v_sqrt_f32_e32 v67, v62
	v_exp_f32_e32 v62, v51
	v_mul_f32_e32 v51, v65, v66
	v_mul_f32_e32 v63, v63, v64
	v_mul_f32_e32 v51, v51, v67
	v_fma_f32 v66, -v62, v62, 1.0
	v_max_f32_e32 v66, 0, v66
	v_sqrt_f32_e32 v66, v66
	v_mul_f32_e32 v67, 0xbfb8aa3b, v181
	v_fmamk_f32 v20, v20, 0xbfb8aa3b, v67
	v_lshlrev_b32_e32 v65, 16, v110
	v_mul_f32_e32 v63, v63, v66
	v_mul_f32_e32 v66, 0xbfb8aa3b, v180
	v_fmamk_f32 v28, v28, 0xbfb8aa3b, v66
	v_min_f32_e32 v28, 0x42700000, v28
	v_min_f32_e32 v20, 0x42700000, v20
	v_mul_f32_e32 v51, v51, v65
	v_mul_f32_e32 v65, 0xbfb8aa3b, v182
	v_exp_f32_e32 v28, v28
	v_exp_f32_e32 v20, v20
	v_exp_f32_e32 v65, v65
	v_lshlrev_b32_e32 v64, 16, v109
	v_add_f32_e32 v28, 1.0, v28
	v_add_f32_e32 v20, 1.0, v20
	v_add_f32_e32 v65, 1.0, v65
	v_mul_f32_e32 v68, v28, v20
	v_log_f32_e32 v65, v65
	v_rcp_f32_e32 v68, v68
	v_mul_f32_e32 v63, v63, v64
	v_fmamk_f32 v21, v21, 0xbfb8aa3b, v67
	v_mul_f32_e32 v64, 0x3f317218, v65
	v_mul_f32_e32 v65, v28, v68
	v_fmamk_f32 v28, v29, 0xbfb8aa3b, v66
	v_min_f32_e32 v28, 0x42700000, v28
	v_min_f32_e32 v21, 0x42700000, v21
	v_exp_f32_e32 v28, v28
	v_exp_f32_e32 v21, v21
	v_mul_f32_e32 v64, 0xc138aa3b, v64
	v_mul_f32_e32 v20, v20, v68
	v_add_f32_e32 v29, 1.0, v28
	v_add_f32_e32 v21, 1.0, v21
	v_mul_f32_e32 v20, v64, v20
	v_mul_f32_e32 v28, v29, v21
	v_exp_f32_e32 v20, v20
	v_rcp_f32_e32 v69, v28
	v_fmamk_f32 v30, v30, 0xbfb8aa3b, v66
	v_fmamk_f32 v22, v22, 0xbfb8aa3b, v67
	v_fma_f32 v28, -v20, v20, 1.0
	v_mul_f32_e32 v21, v21, v69
	v_max_f32_e32 v28, 0, v28
	v_mul_f32_e32 v21, v64, v21
	v_min_f32_e32 v30, 0x42700000, v30
	v_min_f32_e32 v22, 0x42700000, v22
	v_sqrt_f32_e32 v70, v28
	v_exp_f32_e32 v28, v21
	v_exp_f32_e32 v30, v30
	v_exp_f32_e32 v22, v22
	v_lshlrev_b32_e32 v68, 16, v108
	v_mul_f32_e32 v21, v65, v70
	v_fma_f32 v65, -v28, v28, 1.0
	v_add_f32_e32 v30, 1.0, v30
	v_add_f32_e32 v22, 1.0, v22
	v_mul_f32_e32 v21, v21, v68
	v_max_f32_e32 v65, 0, v65
	v_mul_f32_e32 v68, v30, v22
	v_sqrt_f32_e32 v65, v65
	v_rcp_f32_e32 v68, v68
	v_mul_f32_e32 v29, v29, v69
	v_fmamk_f32 v23, v23, 0xbfb8aa3b, v67
	v_mul_f32_e32 v29, v29, v65
	v_mul_f32_e32 v65, v30, v68
	v_fmamk_f32 v30, v31, 0xbfb8aa3b, v66
	v_min_f32_e32 v30, 0x42700000, v30
	v_min_f32_e32 v23, 0x42700000, v23
	v_exp_f32_e32 v30, v30
	v_exp_f32_e32 v23, v23
	v_mul_f32_e32 v22, v22, v68
	v_lshlrev_b32_e32 v69, 16, v107
	v_add_f32_e32 v31, 1.0, v30
	v_add_f32_e32 v23, 1.0, v23
	v_mul_f32_e32 v22, v64, v22
	v_mul_f32_e32 v30, v31, v23
	v_mul_f32_e32 v29, v29, v69
	v_exp_f32_e32 v22, v22
	v_rcp_f32_e32 v69, v30
	v_fmamk_f32 v24, v24, 0xbfb8aa3b, v66
	v_fmamk_f32 v16, v16, 0xbfb8aa3b, v67
	v_fma_f32 v30, -v22, v22, 1.0
	v_mul_f32_e32 v23, v23, v69
	v_max_f32_e32 v30, 0, v30
	v_mul_f32_e32 v23, v64, v23
	v_min_f32_e32 v24, 0x42700000, v24
	v_min_f32_e32 v16, 0x42700000, v16
	v_sqrt_f32_e32 v70, v30
	v_exp_f32_e32 v30, v23
	v_exp_f32_e32 v24, v24
	v_exp_f32_e32 v16, v16
	s_waitcnt lgkmcnt(13)
	v_lshlrev_b32_e32 v68, 16, v106
	v_mul_f32_e32 v23, v65, v70
	v_fma_f32 v65, -v30, v30, 1.0
	v_add_f32_e32 v24, 1.0, v24
	v_add_f32_e32 v16, 1.0, v16
	v_mul_f32_e32 v23, v23, v68
	v_max_f32_e32 v65, 0, v65
	v_mul_f32_e32 v68, v24, v16
	v_sqrt_f32_e32 v65, v65
	v_rcp_f32_e32 v68, v68
	v_mul_f32_e32 v31, v31, v69
	v_fmamk_f32 v17, v17, 0xbfb8aa3b, v67
	v_mul_f32_e32 v31, v31, v65
	v_mul_f32_e32 v65, v24, v68
	v_fmamk_f32 v24, v25, 0xbfb8aa3b, v66
	v_min_f32_e32 v24, 0x42700000, v24
	v_min_f32_e32 v17, 0x42700000, v17
	v_exp_f32_e32 v24, v24
	v_exp_f32_e32 v17, v17
	v_mul_f32_e32 v16, v16, v68
	s_waitcnt lgkmcnt(12)
	v_lshlrev_b32_e32 v69, 16, v105
	v_add_f32_e32 v25, 1.0, v24
	v_add_f32_e32 v17, 1.0, v17
	v_mul_f32_e32 v16, v64, v16
	v_mul_f32_e32 v24, v25, v17
	v_mul_f32_e32 v31, v31, v69
	v_exp_f32_e32 v16, v16
	v_rcp_f32_e32 v69, v24
	v_fmamk_f32 v26, v26, 0xbfb8aa3b, v66
	v_fmamk_f32 v18, v18, 0xbfb8aa3b, v67
	v_fma_f32 v24, -v16, v16, 1.0
	v_mul_f32_e32 v17, v17, v69
	v_max_f32_e32 v24, 0, v24
	v_mul_f32_e32 v17, v64, v17
	v_sqrt_f32_e32 v70, v24
	v_exp_f32_e32 v24, v17
	v_min_f32_e32 v26, 0x42700000, v26
	v_min_f32_e32 v18, 0x42700000, v18
	v_mul_f32_e32 v17, v65, v70
	v_fma_f32 v65, -v24, v24, 1.0
	v_exp_f32_e32 v26, v26
	v_exp_f32_e32 v18, v18
	v_max_f32_e32 v65, 0, v65
	v_sqrt_f32_e32 v65, v65
	s_waitcnt lgkmcnt(11)
	v_lshlrev_b32_e32 v68, 16, v104
	v_mul_f32_e32 v17, v17, v68
	v_add_f32_e32 v68, 1.0, v26
	v_add_f32_e32 v18, 1.0, v18
	v_mul_f32_e32 v25, v25, v69
	v_mul_f32_e32 v26, v68, v18
	v_rcp_f32_e32 v69, v26
	s_waitcnt lgkmcnt(10)
	v_lshlrev_b32_e32 v26, 16, v103
	v_mul_f32_e32 v25, v25, v65
	v_fmac_f32_e32 v66, 0xbfb8aa3b, v27
	v_fmac_f32_e32 v67, 0xbfb8aa3b, v19
	v_mul_f32_e32 v25, v25, v26
	v_min_f32_e32 v26, 0x42700000, v66
	v_min_f32_e32 v19, 0x42700000, v67
	v_exp_f32_e32 v26, v26
	v_exp_f32_e32 v19, v19
	v_mul_f32_e32 v18, v18, v69
	v_mul_f32_e32 v18, v64, v18
	v_add_f32_e32 v27, 1.0, v26
	v_add_f32_e32 v19, 1.0, v19
	v_mul_f32_e32 v26, v27, v19
	v_exp_f32_e32 v18, v18
	v_rcp_f32_e32 v65, v26
	v_mul_f32_e32 v67, 0xbfb8aa3b, v179
	v_fmamk_f32 v12, v12, 0xbfb8aa3b, v67
	v_fma_f32 v26, -v18, v18, 1.0
	v_mul_f32_e32 v19, v19, v65
	v_max_f32_e32 v26, 0, v26
	v_mul_f32_e32 v19, v64, v19
	v_sqrt_f32_e32 v66, v26
	v_exp_f32_e32 v26, v19
	v_mul_f32_e32 v19, v68, v69
	v_mul_f32_e32 v27, v27, v65
	v_mul_f32_e32 v19, v19, v66
	v_fma_f32 v66, -v26, v26, 1.0
	v_max_f32_e32 v66, 0, v66
	v_sqrt_f32_e32 v66, v66
	v_min_f32_e32 v12, 0x42700000, v12
	v_mul_f32_e32 v65, 0xbfb8aa3b, v177
	v_exp_f32_e32 v12, v12
	v_mul_f32_e32 v27, v27, v66
	v_mul_f32_e32 v66, 0xbfb8aa3b, v178
	v_fmamk_f32 v8, v8, 0xbfb8aa3b, v66
	v_min_f32_e32 v8, 0x42700000, v8
	v_exp_f32_e32 v8, v8
	v_exp_f32_e32 v65, v65
	v_add_f32_e32 v12, 1.0, v12
	s_waitcnt lgkmcnt(9)
	v_lshlrev_b32_e32 v64, 16, v102
	v_add_f32_e32 v8, 1.0, v8
	v_add_f32_e32 v65, 1.0, v65
	v_mul_f32_e32 v68, v8, v12
	v_log_f32_e32 v65, v65
	v_rcp_f32_e32 v68, v68
	v_mul_f32_e32 v19, v19, v64
	s_waitcnt lgkmcnt(8)
	v_lshlrev_b32_e32 v64, 16, v101
	v_mul_f32_e32 v27, v27, v64
	v_mul_f32_e32 v64, 0x3f317218, v65
	v_mul_f32_e32 v65, v8, v68
	v_fmamk_f32 v8, v9, 0xbfb8aa3b, v66
	v_min_f32_e32 v8, 0x42700000, v8
	v_exp_f32_e32 v9, v8
	v_fmamk_f32 v8, v13, 0xbfb8aa3b, v67
	v_min_f32_e32 v8, 0x42700000, v8
	v_exp_f32_e32 v13, v8
	v_mul_f32_e32 v64, 0xc138aa3b, v64
	v_mul_f32_e32 v12, v12, v68
	v_add_f32_e32 v69, 1.0, v9
	v_add_f32_e32 v9, 1.0, v13
	v_mul_f32_e32 v8, v64, v12
	v_mul_f32_e32 v12, v69, v9
	v_exp_f32_e32 v8, v8
	v_rcp_f32_e32 v13, v12
	v_fmamk_f32 v10, v10, 0xbfb8aa3b, v66
	v_fmamk_f32 v14, v14, 0xbfb8aa3b, v67
	v_fma_f32 v12, -v8, v8, 1.0
	v_mul_f32_e32 v9, v9, v13
	v_max_f32_e32 v12, 0, v12
	v_mul_f32_e32 v9, v64, v9
	v_min_f32_e32 v10, 0x42700000, v10
	v_min_f32_e32 v14, 0x42700000, v14
	v_sqrt_f32_e32 v70, v12
	v_exp_f32_e32 v12, v9
	v_exp_f32_e32 v10, v10
	v_exp_f32_e32 v14, v14
	s_waitcnt lgkmcnt(7)
	v_lshlrev_b32_e32 v68, 16, v100
	v_mul_f32_e32 v9, v65, v70
	v_fma_f32 v65, -v12, v12, 1.0
	v_add_f32_e32 v10, 1.0, v10
	v_add_f32_e32 v14, 1.0, v14
	v_mul_f32_e32 v9, v9, v68
	v_max_f32_e32 v65, 0, v65
	v_mul_f32_e32 v68, v10, v14
	v_sqrt_f32_e32 v65, v65
	v_rcp_f32_e32 v68, v68
	v_mul_f32_e32 v13, v69, v13
	s_waitcnt lgkmcnt(6)
	v_lshlrev_b32_e32 v69, 16, v99
	v_mul_f32_e32 v13, v13, v65
	v_mul_f32_e32 v65, v10, v68
	v_fmamk_f32 v10, v11, 0xbfb8aa3b, v66
	v_min_f32_e32 v10, 0x42700000, v10
	v_exp_f32_e32 v11, v10
	v_fmamk_f32 v10, v15, 0xbfb8aa3b, v67
	v_min_f32_e32 v10, 0x42700000, v10
	v_exp_f32_e32 v15, v10
	v_mul_f32_e32 v13, v13, v69
	v_mul_f32_e32 v14, v14, v68
	v_add_f32_e32 v69, 1.0, v11
	v_add_f32_e32 v11, 1.0, v15
	v_mul_f32_e32 v10, v64, v14
	v_mul_f32_e32 v14, v69, v11
	v_exp_f32_e32 v10, v10
	v_rcp_f32_e32 v15, v14
	v_fmamk_f32 v0, v0, 0xbfb8aa3b, v66
	v_fmamk_f32 v4, v4, 0xbfb8aa3b, v67
	v_fma_f32 v14, -v10, v10, 1.0
	v_mul_f32_e32 v11, v11, v15
	v_max_f32_e32 v14, 0, v14
	v_mul_f32_e32 v11, v64, v11
	v_min_f32_e32 v0, 0x42700000, v0
	v_min_f32_e32 v4, 0x42700000, v4
	v_sqrt_f32_e32 v70, v14
	v_exp_f32_e32 v14, v11
	v_exp_f32_e32 v0, v0
	v_exp_f32_e32 v4, v4
	s_waitcnt lgkmcnt(5)
	v_lshlrev_b32_e32 v68, 16, v98
	v_mul_f32_e32 v11, v65, v70
	v_fma_f32 v65, -v14, v14, 1.0
	v_add_f32_e32 v0, 1.0, v0
	v_add_f32_e32 v4, 1.0, v4
	v_mul_f32_e32 v11, v11, v68
	v_max_f32_e32 v65, 0, v65
	v_mul_f32_e32 v68, v0, v4
	v_sqrt_f32_e32 v65, v65
	v_rcp_f32_e32 v68, v68
	v_mul_f32_e32 v15, v69, v15
	s_waitcnt lgkmcnt(4)
	v_lshlrev_b32_e32 v69, 16, v97
	v_mul_f32_e32 v15, v15, v65
	v_mul_f32_e32 v65, v0, v68
	v_fmamk_f32 v0, v1, 0xbfb8aa3b, v66
	v_min_f32_e32 v0, 0x42700000, v0
	v_exp_f32_e32 v1, v0
	v_fmamk_f32 v0, v5, 0xbfb8aa3b, v67
	v_min_f32_e32 v0, 0x42700000, v0
	v_exp_f32_e32 v5, v0
	v_mul_f32_e32 v15, v15, v69
	v_mul_f32_e32 v4, v4, v68
	v_add_f32_e32 v69, 1.0, v1
	v_add_f32_e32 v1, 1.0, v5
	v_mul_f32_e32 v0, v64, v4
	v_mul_f32_e32 v4, v69, v1
	v_exp_f32_e32 v0, v0
	v_rcp_f32_e32 v5, v4
	v_fmamk_f32 v2, v2, 0xbfb8aa3b, v66
	v_fmamk_f32 v6, v6, 0xbfb8aa3b, v67
	v_fma_f32 v4, -v0, v0, 1.0
	v_mul_f32_e32 v1, v1, v5
	v_max_f32_e32 v4, 0, v4
	v_mul_f32_e32 v1, v64, v1
	v_sqrt_f32_e32 v70, v4
	v_exp_f32_e32 v4, v1
	v_min_f32_e32 v2, 0x42700000, v2
	v_min_f32_e32 v6, 0x42700000, v6
	v_mul_f32_e32 v1, v65, v70
	v_fma_f32 v65, -v4, v4, 1.0
	v_exp_f32_e32 v2, v2
	v_exp_f32_e32 v6, v6
	v_max_f32_e32 v65, 0, v65
	v_sqrt_f32_e32 v65, v65
	s_waitcnt lgkmcnt(3)
	v_lshlrev_b32_e32 v68, 16, v96
	v_mul_f32_e32 v1, v1, v68
	v_add_f32_e32 v68, 1.0, v2
	v_add_f32_e32 v2, 1.0, v6
	v_mul_f32_e32 v5, v69, v5
	v_mul_f32_e32 v6, v68, v2
	v_rcp_f32_e32 v69, v6
	s_waitcnt lgkmcnt(2)
	v_lshlrev_b32_e32 v6, 16, v95
	v_mul_f32_e32 v5, v5, v65
	v_fmac_f32_e32 v66, 0xbfb8aa3b, v3
	v_fmac_f32_e32 v67, 0xbfb8aa3b, v7
	v_mul_f32_e32 v5, v5, v6
	v_min_f32_e32 v3, 0x42700000, v66
	v_min_f32_e32 v6, 0x42700000, v67
	v_exp_f32_e32 v3, v3
	v_exp_f32_e32 v6, v6
	v_mul_f32_e32 v2, v2, v69
	v_mul_f32_e32 v2, v64, v2
	v_add_f32_e32 v7, 1.0, v3
	v_add_f32_e32 v3, 1.0, v6
	v_mul_f32_e32 v6, v7, v3
	v_exp_f32_e32 v2, v2
	v_rcp_f32_e32 v65, v6
	s_waitcnt lgkmcnt(0)
	s_barrier
	v_fma_f32 v6, -v2, v2, 1.0
	v_mul_f32_e32 v3, v3, v65
	v_max_f32_e32 v6, 0, v6
	v_mul_f32_e32 v3, v64, v3
	v_sqrt_f32_e32 v66, v6
	v_exp_f32_e32 v6, v3
	v_mul_f32_e32 v3, v68, v69
	v_lshlrev_b32_e32 v64, 16, v93
	v_mul_f32_e32 v3, v3, v66
	v_fma_f32 v66, -v6, v6, 1.0
	v_max_f32_e32 v66, 0, v66
	v_sqrt_f32_e32 v66, v66
	v_mul_f32_e32 v7, v7, v65
	v_mul_f32_e32 v3, v3, v64
	v_lshlrev_b32_e32 v64, 16, v94
	v_mul_f32_e32 v7, v7, v66
	v_mul_f32_e32 v7, v7, v64
	v_or_b32_e32 v64, v176, v175
	v_lshlrev_b32_e32 v65, 11, v91
	v_lshlrev_b32_e32 v64, 3, v64
	v_add3_u32 v64, 0, v65, v64
	ds_write2_b64 v64, v[32:33], v[52:53] offset1:16
	v_add_u32_e32 v32, 0x800, v64
	ds_write2_b64 v32, v[34:35], v[54:55] offset1:16
	v_add_u32_e32 v33, 0x1000, v64
	v_add_u32_e32 v34, 0x1800, v64
	ds_write2_b64 v33, v[36:37], v[56:57] offset1:16
	ds_write2_b64 v34, v[38:39], v[58:59] offset1:16
	v_add_u32_e32 v35, 0x8000, v64
	v_add_u32_e32 v36, 0x8800, v64
	v_add_u32_e32 v37, 0x9000, v64
	v_add_u32_e32 v38, 0x9800, v64
	ds_write2_b64 v35, v[40:41], v[48:49] offset1:16
	ds_write2_b64 v36, v[42:43], v[60:61] offset1:16
	ds_write2_b64 v37, v[44:45], v[50:51] offset1:16
	ds_write2_b64 v38, v[46:47], v[62:63] offset1:16
	ds_write2_b64 v64, v[20:21], v[8:9] offset0:32 offset1:48
	ds_write2_b64 v32, v[28:29], v[12:13] offset0:32 offset1:48
	ds_write2_b64 v33, v[22:23], v[10:11] offset0:32 offset1:48
	ds_write2_b64 v34, v[30:31], v[14:15] offset0:32 offset1:48
	ds_write2_b64 v35, v[16:17], v[0:1] offset0:32 offset1:48
	ds_write2_b64 v36, v[24:25], v[4:5] offset0:32 offset1:48
	ds_write2_b64 v37, v[18:19], v[2:3] offset0:32 offset1:48
	ds_write2_b64 v38, v[26:27], v[6:7] offset0:32 offset1:48
	s_waitcnt lgkmcnt(0)
	s_barrier
	s_and_saveexec_b64 s[10:11], vcc
	s_cbranch_execz .LBB0_845
	v_lshl_add_u32 v0, v173, 3, 0
	ds_read2st64_b64 v[36:39], v0 offset1:4
	ds_read2st64_b64 v[40:43], v0 offset0:8 offset1:12
	ds_read2st64_b64 v[44:47], v0 offset0:16 offset1:20
	ds_read2st64_b64 v[48:51], v0 offset0:24 offset1:28
	ds_read2st64_b64 v[52:55], v0 offset0:32 offset1:36
	ds_read2st64_b64 v[56:59], v0 offset0:40 offset1:44
	ds_read2st64_b64 v[60:63], v0 offset0:48 offset1:52
	ds_read2st64_b64 v[64:67], v0 offset0:56 offset1:60
	v_readlane_b32 s1, v243, 56
	s_load_dwordx2 s[6:7], s[6:7], 0xf8
	s_lshl_b32 s0, s70, 7
	v_add_u32_e32 v68, 0x10000, v0
	s_lshl_b32 s1, s1, 6
	s_add_i32 s1, s1, s0
	v_readlane_b32 s0, v244, 0
	s_or_b32 s12, s1, s0
	s_mov_b32 s3, 0x4460000
	s_waitcnt vmcnt(7) lgkmcnt(0)
	v_fmac_f32_e32 v37, v92, v36
	v_fmac_f32_e32 v39, v37, v38
	v_fmac_f32_e32 v41, v39, v40
	v_fmac_f32_e32 v43, v41, v42
	v_fmac_f32_e32 v45, v43, v44
	v_fmac_f32_e32 v47, v45, v46
	v_fmac_f32_e32 v49, v47, v48
	v_fmac_f32_e32 v51, v49, v50
	ds_write2st64_b32 v0, v37, v39 offset1:8
	ds_write2st64_b32 v0, v41, v43 offset0:16 offset1:24
	ds_write2st64_b32 v0, v45, v47 offset0:32 offset1:40
	ds_write2st64_b32 v0, v49, v51 offset0:48 offset1:56
	s_mov_b32 s0, s12
	s_ashr_i32 s1, s0, 31
	s_lshl_b64 s[0:1], s[0:1], 12
	s_add_u32 s0, s6, s0
	s_addc_u32 s1, s7, s1
	v_lshl_add_u64 v[2:3], s[0:1], 0, v[184:185]
	v_add_co_u32_e32 v2, vcc, s3, v2
	s_nop 1
	v_addc_co_u32_e32 v3, vcc, 0, v3, vcc
	global_store_dword v[2:3], v51, off
	ds_read2st64_b64 v[36:39], v0 offset0:64 offset1:68
	ds_read2st64_b64 v[40:43], v0 offset0:72 offset1:76
	ds_read2st64_b64 v[44:47], v0 offset0:80 offset1:84
	ds_read2st64_b64 v[48:51], v0 offset0:88 offset1:92
	s_waitcnt vmcnt(7) lgkmcnt(0)
	v_fmac_f32_e32 v53, v90, v52
	v_fmac_f32_e32 v55, v53, v54
	v_fmac_f32_e32 v57, v55, v56
	v_fmac_f32_e32 v59, v57, v58
	v_fmac_f32_e32 v61, v59, v60
	v_fmac_f32_e32 v63, v61, v62
	v_fmac_f32_e32 v65, v63, v64
	v_fmac_f32_e32 v67, v65, v66
	ds_write2st64_b32 v0, v53, v55 offset0:64 offset1:72
	ds_write2st64_b32 v0, v57, v59 offset0:80 offset1:88
	ds_write2st64_b32 v0, v61, v63 offset0:96 offset1:104
	ds_write2st64_b32 v0, v65, v67 offset0:112 offset1:120
	s_or_b32 s0, s12, 1
	s_ashr_i32 s1, s0, 31
	s_lshl_b64 s[0:1], s[0:1], 12
	s_add_u32 s0, s6, s0
	s_addc_u32 s1, s7, s1
	v_lshl_add_u64 v[2:3], s[0:1], 0, v[184:185]
	v_add_co_u32_e32 v2, vcc, s3, v2
	s_nop 1
	v_addc_co_u32_e32 v3, vcc, 0, v3, vcc
	global_store_dword v[2:3], v67, off
	ds_read2st64_b64 v[52:55], v0 offset0:96 offset1:100
	ds_read2st64_b64 v[56:59], v0 offset0:104 offset1:108
	ds_read2st64_b64 v[60:63], v0 offset0:112 offset1:116
	ds_read2st64_b64 v[64:67], v0 offset0:120 offset1:124
	s_waitcnt vmcnt(7) lgkmcnt(8)
	v_fmac_f32_e32 v37, v89, v36
	v_fmac_f32_e32 v39, v37, v38
	v_fmac_f32_e32 v41, v39, v40
	v_fmac_f32_e32 v43, v41, v42
	v_fmac_f32_e32 v45, v43, v44
	v_fmac_f32_e32 v47, v45, v46
	v_fmac_f32_e32 v49, v47, v48
	v_fmac_f32_e32 v51, v49, v50
	ds_write2st64_b32 v0, v37, v39 offset0:128 offset1:136
	ds_write2st64_b32 v0, v41, v43 offset0:144 offset1:152
	ds_write2st64_b32 v0, v45, v47 offset0:160 offset1:168
	ds_write2st64_b32 v0, v49, v51 offset0:176 offset1:184
	s_or_b32 s0, s12, 2
	s_ashr_i32 s1, s0, 31
	s_lshl_b64 s[0:1], s[0:1], 12
	s_add_u32 s0, s6, s0
	s_addc_u32 s1, s7, s1
	v_lshl_add_u64 v[2:3], s[0:1], 0, v[184:185]
	v_add_co_u32_e32 v2, vcc, s3, v2
	s_nop 1
	v_addc_co_u32_e32 v3, vcc, 0, v3, vcc
	global_store_dword v[2:3], v51, off
	ds_read2st64_b64 v[36:39], v0 offset0:128 offset1:132
	ds_read2st64_b64 v[40:43], v0 offset0:136 offset1:140
	ds_read2st64_b64 v[44:47], v0 offset0:144 offset1:148
	ds_read2st64_b64 v[48:51], v0 offset0:152 offset1:156
	s_waitcnt vmcnt(7) lgkmcnt(8)
	v_fmac_f32_e32 v53, v88, v52
	v_fmac_f32_e32 v55, v53, v54
	v_fmac_f32_e32 v57, v55, v56
	v_fmac_f32_e32 v59, v57, v58
	v_fmac_f32_e32 v61, v59, v60
	v_fmac_f32_e32 v63, v61, v62
	v_fmac_f32_e32 v65, v63, v64
	v_fmac_f32_e32 v67, v65, v66
	ds_write2st64_b32 v0, v53, v55 offset0:192 offset1:200
	ds_write2st64_b32 v0, v57, v59 offset0:208 offset1:216
	ds_write2st64_b32 v0, v61, v63 offset0:224 offset1:232
	ds_write2st64_b32 v0, v65, v67 offset0:240 offset1:248
	s_or_b32 s0, s12, 3
	s_ashr_i32 s1, s0, 31
	s_lshl_b64 s[0:1], s[0:1], 12
	s_add_u32 s0, s6, s0
	s_addc_u32 s1, s7, s1
	v_lshl_add_u64 v[2:3], s[0:1], 0, v[184:185]
	v_add_co_u32_e32 v2, vcc, s3, v2
	s_nop 1
	v_addc_co_u32_e32 v3, vcc, 0, v3, vcc
	global_store_dword v[2:3], v67, off
	ds_read2st64_b64 v[52:55], v0 offset0:160 offset1:164
	ds_read2st64_b64 v[56:59], v0 offset0:168 offset1:172
	ds_read2st64_b64 v[60:63], v0 offset0:176 offset1:180
	ds_read2st64_b64 v[64:67], v0 offset0:184 offset1:188
	s_waitcnt vmcnt(7) lgkmcnt(8)
	v_fmac_f32_e32 v37, v87, v36
	v_fmac_f32_e32 v39, v37, v38
	v_fmac_f32_e32 v41, v39, v40
	v_fmac_f32_e32 v43, v41, v42
	v_fmac_f32_e32 v45, v43, v44
	v_fmac_f32_e32 v47, v45, v46
	v_fmac_f32_e32 v49, v47, v48
	v_fmac_f32_e32 v51, v49, v50
	ds_write2st64_b32 v68, v37, v39 offset1:8
	ds_write2st64_b32 v68, v41, v43 offset0:16 offset1:24
	ds_write2st64_b32 v68, v45, v47 offset0:32 offset1:40
	ds_write2st64_b32 v68, v49, v51 offset0:48 offset1:56
	s_or_b32 s0, s12, 4
	s_ashr_i32 s1, s0, 31
	s_lshl_b64 s[0:1], s[0:1], 12
	s_add_u32 s0, s6, s0
	s_addc_u32 s1, s7, s1
	v_lshl_add_u64 v[2:3], s[0:1], 0, v[184:185]
	v_add_co_u32_e32 v2, vcc, s3, v2
	s_nop 1
	v_addc_co_u32_e32 v3, vcc, 0, v3, vcc
	global_store_dword v[2:3], v51, off
	ds_read2st64_b64 v[36:39], v0 offset0:192 offset1:196
	ds_read2st64_b64 v[40:43], v0 offset0:200 offset1:204
	ds_read2st64_b64 v[44:47], v0 offset0:208 offset1:212
	ds_read2st64_b64 v[48:51], v0 offset0:216 offset1:220
	s_waitcnt vmcnt(7) lgkmcnt(8)
	v_fmac_f32_e32 v53, v86, v52
	v_fmac_f32_e32 v55, v53, v54
	v_fmac_f32_e32 v57, v55, v56
	v_fmac_f32_e32 v59, v57, v58
	v_fmac_f32_e32 v61, v59, v60
	v_fmac_f32_e32 v63, v61, v62
	v_fmac_f32_e32 v65, v63, v64
	v_fmac_f32_e32 v67, v65, v66
	ds_write2st64_b32 v68, v53, v55 offset0:64 offset1:72
	ds_write2st64_b32 v68, v57, v59 offset0:80 offset1:88
	ds_write2st64_b32 v68, v61, v63 offset0:96 offset1:104
	ds_write2st64_b32 v68, v65, v67 offset0:112 offset1:120
	s_or_b32 s0, s12, 5
	s_ashr_i32 s1, s0, 31
	s_lshl_b64 s[0:1], s[0:1], 12
	s_add_u32 s0, s6, s0
	s_addc_u32 s1, s7, s1
	v_lshl_add_u64 v[2:3], s[0:1], 0, v[184:185]
	v_add_co_u32_e32 v2, vcc, s3, v2
	s_nop 1
	v_addc_co_u32_e32 v3, vcc, 0, v3, vcc
	global_store_dword v[2:3], v67, off
	ds_read2st64_b64 v[52:55], v0 offset0:224 offset1:228
	ds_read2st64_b64 v[56:59], v0 offset0:232 offset1:236
	ds_read2st64_b64 v[60:63], v0 offset0:240 offset1:244
	ds_read2st64_b64 v[64:67], v0 offset0:248 offset1:252
	s_waitcnt vmcnt(7) lgkmcnt(8)
	v_fmac_f32_e32 v37, v85, v36
	v_fmac_f32_e32 v39, v37, v38
	v_fmac_f32_e32 v41, v39, v40
	v_fmac_f32_e32 v43, v41, v42
	v_fmac_f32_e32 v45, v43, v44
	v_fmac_f32_e32 v47, v45, v46
	v_fmac_f32_e32 v49, v47, v48
	v_fmac_f32_e32 v51, v49, v50
	ds_write2st64_b32 v68, v37, v39 offset0:128 offset1:136
	ds_write2st64_b32 v68, v41, v43 offset0:144 offset1:152
	ds_write2st64_b32 v68, v45, v47 offset0:160 offset1:168
	ds_write2st64_b32 v68, v49, v51 offset0:176 offset1:184
	s_or_b32 s0, s12, 6
	s_ashr_i32 s1, s0, 31
	s_lshl_b64 s[0:1], s[0:1], 12
	s_add_u32 s0, s6, s0
	s_addc_u32 s1, s7, s1
	v_lshl_add_u64 v[2:3], s[0:1], 0, v[184:185]
	v_add_co_u32_e32 v2, vcc, s3, v2
	s_nop 1
	v_addc_co_u32_e32 v3, vcc, 0, v3, vcc
	global_store_dword v[2:3], v51, off
	s_waitcnt vmcnt(7) lgkmcnt(4)
	v_fmac_f32_e32 v53, v84, v52
	v_fmac_f32_e32 v55, v53, v54
	v_fmac_f32_e32 v57, v55, v56
	v_fmac_f32_e32 v59, v57, v58
	v_fmac_f32_e32 v61, v59, v60
	v_fmac_f32_e32 v63, v61, v62
	v_fmac_f32_e32 v65, v63, v64
	v_fmac_f32_e32 v67, v65, v66
	ds_write2st64_b32 v68, v53, v55 offset0:192 offset1:200
	ds_write2st64_b32 v68, v57, v59 offset0:208 offset1:216
	ds_write2st64_b32 v68, v61, v63 offset0:224 offset1:232
	ds_write2st64_b32 v68, v65, v67 offset0:240 offset1:248
	s_or_b32 s0, s12, 7
	s_ashr_i32 s1, s0, 31
	s_lshl_b64 s[0:1], s[0:1], 12
	s_add_u32 s0, s6, s0
	s_addc_u32 s1, s7, s1
	v_lshl_add_u64 v[2:3], s[0:1], 0, v[184:185]
	v_add_co_u32_e32 v2, vcc, s3, v2
	s_nop 1
	v_addc_co_u32_e32 v3, vcc, 0, v3, vcc
	global_store_dword v[2:3], v67, off
.LBB0_845:
	s_or_b64 exec, exec, s[10:11]
	s_lshl_b32 s0, s84, 1
	v_and_b32_e32 v8, 63, v173
	s_add_u32 s0, s8, s0
	s_addc_u32 s1, s9, 0
	v_lshlrev_b32_e32 v2, 14, v172
	v_lshlrev_b32_e32 v9, 4, v8
	v_mov_b64_e32 v[0:1], s[0:1]
	v_add3_u32 v10, 0, v2, v9
	s_waitcnt lgkmcnt(0)
	s_barrier
	ds_read_b128 v[36:39], v10
	ds_read_b128 v[40:43], v10 offset:1024
	ds_read_b128 v[44:47], v10 offset:2048
	ds_read_b128 v[48:51], v10 offset:3072
	ds_read_b128 v[52:55], v10 offset:4096
	ds_read_b128 v[56:59], v10 offset:5120
	ds_read_b128 v[60:63], v10 offset:6144
	ds_read_b128 v[64:67], v10 offset:7168
	ds_read_b128 v[68:71], v10 offset:8192
	ds_read_b128 v[72:75], v10 offset:9216
	ds_read_b128 v[76:79], v10 offset:10240
	ds_read_b128 v[80:83], v10 offset:11264
	ds_read_b128 v[84:87], v10 offset:12288
	ds_read_b128 v[88:91], v10 offset:13312
	ds_read_b128 v[92:95], v10 offset:14336
	ds_read_b128 v[96:99], v10 offset:15360
	v_lshlrev_b32_e32 v184, 2, v8
	v_readlane_b32 s3, v245, 63
	v_mad_i64_i32 v[6:7], s[0:1], v174, s68, v[0:1]
	v_lshl_add_u64 v[6:7], v[6:7], 0, v[184:185]
	s_waitcnt lgkmcnt(14)
	v_cvt_pk_bf16_f32 v3, v36, v38
	v_cvt_pk_bf16_f32 v4, v40, v42
	global_store_dword v[6:7], v3, off
	global_store_dword v[6:7], v4, off offset:256
	v_or_b32_e32 v2, 1, v137
	v_add_u32_e32 v2, s3, v2
	v_mad_i64_i32 v[6:7], s[0:1], v2, s68, v[0:1]
	v_lshl_add_u64 v[6:7], v[6:7], 0, v[184:185]
	s_waitcnt lgkmcnt(12)
	v_cvt_pk_bf16_f32 v3, v44, v46
	v_cvt_pk_bf16_f32 v4, v48, v50
	global_store_dword v[6:7], v3, off
	global_store_dword v[6:7], v4, off offset:256
	v_or_b32_e32 v2, 2, v137
	v_add_u32_e32 v2, s3, v2
	v_mad_i64_i32 v[6:7], s[0:1], v2, s68, v[0:1]
	v_lshl_add_u64 v[6:7], v[6:7], 0, v[184:185]
	s_waitcnt lgkmcnt(10)
	v_cvt_pk_bf16_f32 v3, v52, v54
	v_cvt_pk_bf16_f32 v4, v56, v58
	global_store_dword v[6:7], v3, off
	global_store_dword v[6:7], v4, off offset:256
	v_or_b32_e32 v2, 3, v137
	v_add_u32_e32 v2, s3, v2
	v_mad_i64_i32 v[6:7], s[0:1], v2, s68, v[0:1]
	v_lshl_add_u64 v[6:7], v[6:7], 0, v[184:185]
	s_waitcnt lgkmcnt(8)
	v_cvt_pk_bf16_f32 v3, v60, v62
	v_cvt_pk_bf16_f32 v4, v64, v66
	global_store_dword v[6:7], v3, off
	global_store_dword v[6:7], v4, off offset:256
	v_or_b32_e32 v2, 4, v137
	v_add_u32_e32 v2, s3, v2
	v_mad_i64_i32 v[6:7], s[0:1], v2, s68, v[0:1]
	v_lshl_add_u64 v[6:7], v[6:7], 0, v[184:185]
	s_waitcnt lgkmcnt(6)
	v_cvt_pk_bf16_f32 v3, v68, v70
	v_cvt_pk_bf16_f32 v4, v72, v74
	global_store_dword v[6:7], v3, off
	global_store_dword v[6:7], v4, off offset:256
	v_or_b32_e32 v2, 5, v137
	v_add_u32_e32 v2, s3, v2
	v_mad_i64_i32 v[6:7], s[0:1], v2, s68, v[0:1]
	v_lshl_add_u64 v[6:7], v[6:7], 0, v[184:185]
	s_waitcnt lgkmcnt(4)
	v_cvt_pk_bf16_f32 v3, v76, v78
	v_cvt_pk_bf16_f32 v4, v80, v82
	global_store_dword v[6:7], v3, off
	global_store_dword v[6:7], v4, off offset:256
	v_or_b32_e32 v2, 6, v137
	v_add_u32_e32 v2, s3, v2
	v_mad_i64_i32 v[6:7], s[0:1], v2, s68, v[0:1]
	v_lshl_add_u64 v[6:7], v[6:7], 0, v[184:185]
	s_waitcnt lgkmcnt(2)
	v_cvt_pk_bf16_f32 v3, v84, v86
	v_cvt_pk_bf16_f32 v4, v88, v90
	global_store_dword v[6:7], v3, off
	global_store_dword v[6:7], v4, off offset:256
	v_or_b32_e32 v2, 7, v137
	v_add_u32_e32 v2, s3, v2
	v_mad_i64_i32 v[6:7], s[0:1], v2, s68, v[0:1]
	v_lshl_add_u64 v[6:7], v[6:7], 0, v[184:185]
	s_waitcnt lgkmcnt(0)
	v_cvt_pk_bf16_f32 v3, v92, v94
	v_cvt_pk_bf16_f32 v4, v96, v98
	global_store_dword v[6:7], v3, off
	global_store_dword v[6:7], v4, off offset:256
	s_barrier
